# RWKV record LDS-DMA loads marked nt
# baseline (speedup 1.0000x reference)
.Lrw_task:
	s_cmp_ge_u32 s7, 0x400
	s_cbranch_scc1 .Lrw_done
	s_and_b32 s24, s7, 15
	s_bfe_u32 s26, s7, 0x40004
	s_bfe_u32 s32, s7, 0x10008
	s_lshr_b32 s36, s7, 9
	s_lshl_b32 s3, s32, 4
	s_add_u32 s3, s3, s26
	s_lshl_b32 s3, s3, 22
	s_add_u32 s10, s92, s3
	s_addc_u32 s11, s93, 0
	s_add_u32 s10, s10, 0xf400000
	s_addc_u32 s11, s11, 0
	s_lshl_b32 s3, s32, 23
	s_lshl_b32 s37, s26, 7
	s_add_u32 s3, s3, s37
	s_add_u32 s12, s92, s3
	s_addc_u32 s13, s93, 0
	s_lshl_b32 s3, s24, 3
	v_lshl_add_u32 v8, v4, 1, s3
	s_lshl_b32 s37, s24, 4
	s_lshl_b32 s39, s6, 12
	s_cmp_lg_u32 s36, 0
	s_cbranch_scc1 .Lrw_bwd
	s_add_u32 s12, s12, 0x2000000
	s_addc_u32 s13, s13, 0
	v_lshl_add_u32 v8, v3, 11, v8
	s_add_u32 s10, s10, s39
	s_addc_u32 s11, s11, 0
	s_mov_b32 s40, s39
	s_mov_b32 s41, 0
	v_lshlrev_b32_e32 v6, 4, v3
	s_add_u32 s3, s37, 0x300
	v_lshl_add_u32 v7, v4, 1, s3
	s_add_u32 s3, s40, s41
	s_and_b32 s3, s3, 0x1ffff
	s_add_u32 s3, s3, 16
	s_mov_b32 m0, s3
	s_nop 0
	global_load_lds_dwordx4 v5, s[10:11] offset:0 nt
	global_load_lds_dwordx4 v5, s[10:11] offset:1024 nt
	global_load_lds_dwordx4 v5, s[10:11] offset:2048 nt
	global_load_lds_dwordx4 v5, s[10:11] offset:3072 nt
	s_add_u32 s10, s10, 0x4000
	s_addc_u32 s11, s11, 0
	s_add_u32 s41, s41, 0x4000
	s_and_b32 s41, s41, 0x1ffff
	s_add_u32 s3, s40, s41
	s_and_b32 s3, s3, 0x1ffff
	s_add_u32 s3, s3, 16
	s_mov_b32 m0, s3
	s_nop 0
	global_load_lds_dwordx4 v5, s[10:11] offset:0 nt
	global_load_lds_dwordx4 v5, s[10:11] offset:1024 nt
	global_load_lds_dwordx4 v5, s[10:11] offset:2048 nt
	global_load_lds_dwordx4 v5, s[10:11] offset:3072 nt
	s_add_u32 s10, s10, 0x4000
	s_addc_u32 s11, s11, 0
	s_add_u32 s41, s41, 0x4000
	s_and_b32 s41, s41, 0x1ffff
	s_add_u32 s3, s40, s41
	s_and_b32 s3, s3, 0x1ffff
	s_add_u32 s3, s3, 16
	s_mov_b32 m0, s3
	s_nop 0
	global_load_lds_dwordx4 v5, s[10:11] offset:0 nt
	global_load_lds_dwordx4 v5, s[10:11] offset:1024 nt
	global_load_lds_dwordx4 v5, s[10:11] offset:2048 nt
	global_load_lds_dwordx4 v5, s[10:11] offset:3072 nt
	s_add_u32 s10, s10, 0x4000
	s_addc_u32 s11, s11, 0
	s_add_u32 s41, s41, 0x4000
	s_and_b32 s41, s41, 0x1ffff
	s_waitcnt vmcnt(0)
	v_mov_b32_e32 v10, 0
	v_mov_b32_e32 v11, 0
	v_mov_b32_e32 v12, 0
	v_mov_b32_e32 v13, 0
	s_mov_b32 s14, 0
	s_add_u32 s3, s15, 3
	v_mov_b32_e32 v69, s3
	ds_write_b32 v23, v69
	s_add_u32 s43, s15, 2
	s_sub_u32 s44, s15, 4
	s_max_i32 s44, s44, 0
	s_mov_b32 s42, 0

.Lrw_ready_d0:
	s_add_u32 s3, s40, s41
	s_and_b32 s3, s3, 0x1ffff
	s_add_u32 s3, s3, 16
	s_mov_b32 m0, s3
	s_nop 0
	global_load_lds_dwordx4 v5, s[10:11] offset:0 nt
	global_load_lds_dwordx4 v5, s[10:11] offset:1024 nt
	global_load_lds_dwordx4 v5, s[10:11] offset:2048 nt
	global_load_lds_dwordx4 v5, s[10:11] offset:3072 nt
	s_add_u32 s10, s10, 0x4000
	s_addc_u32 s11, s11, 0
	s_add_u32 s41, s41, 0x4000
	s_and_b32 s41, s41, 0x1ffff
	ds_read_b64 v[72:73], v6 offset:2064
	ds_read_b128 v[74:77], v6 offset:2320
	ds_read_b128 v[78:81], v6 offset:2576
	ds_read_u16 v82, v7 offset:2064
	v_fma_mix_f32 v14, v10, v26, 0 op_sel:[0,0,0] op_sel_hi:[0,1,0]
	v_fma_mix_f32 v63, v10, v92, 0 op_sel:[0,0,0] op_sel_hi:[0,1,0]
	v_fma_mix_f32 v14, v11, v26, v14 op_sel:[0,1,0] op_sel_hi:[0,1,0]
	v_fma_mix_f32 v63, v11, v92, v63 op_sel:[0,1,0] op_sel_hi:[0,1,0]
	v_fma_mix_f32 v14, v12, v27, v14 op_sel:[0,0,0] op_sel_hi:[0,1,0]
	v_fma_mix_f32 v63, v12, v93, v63 op_sel:[0,0,0] op_sel_hi:[0,1,0]
	v_fma_mix_f32 v14, v13, v27, v14 op_sel:[0,1,0] op_sel_hi:[0,1,0]
	v_fma_mix_f32 v16, v10, v24, 0 op_sel:[0,0,0] op_sel_hi:[0,1,0]
	v_fma_mix_f32 v17, v11, v24, 0 op_sel:[0,1,0] op_sel_hi:[0,1,0]
	v_add_f32_dpp v20, v14, v14 quad_perm:[1,0,3,2] row_mask:0xf bank_mask:0xf bound_ctrl:1
	v_fma_mix_f32 v63, v13, v93, v63 op_sel:[0,1,0] op_sel_hi:[0,1,0]
	v_fma_mix_f32 v18, v12, v25, 0 op_sel:[0,0,0] op_sel_hi:[0,1,0]
	v_add_f32_dpp v20, v20, v20 quad_perm:[2,3,0,1] row_mask:0xf bank_mask:0xf bound_ctrl:1
	v_fma_mix_f32 v19, v13, v25, 0 op_sel:[0,1,0] op_sel_hi:[0,1,0]
	v_fma_mix_f32 v16, v34, v30, v16 op_sel:[0,0,0] op_sel_hi:[1,1,0]
	v_add_f32_dpp v20, v20, v20 row_half_mirror row_mask:0xf bank_mask:0xf bound_ctrl:1
	v_fma_mix_f32 v17, v34, v30, v17 op_sel:[0,1,0] op_sel_hi:[1,1,0]
	v_fma_mix_f32 v18, v34, v31, v18 op_sel:[0,0,0] op_sel_hi:[1,1,0]
	v_add_f32_dpp v20, v20, v20 row_mirror row_mask:0xf bank_mask:0xf bound_ctrl:1
	v_fma_mix_f32 v19, v34, v31, v19 op_sel:[0,1,0] op_sel_hi:[1,1,0]
	v_fma_mix_f32 v10, v20, v28, v16 op_sel:[0,0,0] op_sel_hi:[0,1,0]
	v_fma_mix_f32 v11, v20, v28, v17 op_sel:[0,1,0] op_sel_hi:[0,1,0]
	v_fma_mix_f32 v12, v20, v29, v18 op_sel:[0,0,0] op_sel_hi:[0,1,0]
	v_fma_mix_f32 v13, v20, v29, v19 op_sel:[0,1,0] op_sel_hi:[0,1,0]
	s_waitcnt lgkmcnt(4)
	s_cmp_eq_u32 s14, 0
	s_cbranch_scc1 .Lrw_skip_d0
	v_add_f32_dpp v48, v48, v48 row_ror:8 row_mask:0xf bank_mask:0x3
	v_add_f32_dpp v49, v49, v49 row_ror:8 row_mask:0xf bank_mask:0x3
	v_add_f32_dpp v50, v50, v50 row_ror:8 row_mask:0xf bank_mask:0x3
	v_add_f32_dpp v51, v51, v51 row_ror:8 row_mask:0xf bank_mask:0x3
	v_add_f32_dpp v52, v52, v52 row_ror:8 row_mask:0xf bank_mask:0x3
	v_add_f32_dpp v53, v53, v53 row_ror:8 row_mask:0xf bank_mask:0x3
	v_add_f32_dpp v54, v54, v54 row_ror:8 row_mask:0xf bank_mask:0x3
	v_add_f32_dpp v55, v55, v55 row_ror:8 row_mask:0xf bank_mask:0x3
	v_add_f32_dpp v48, v56, v56 row_ror:8 row_mask:0xf bank_mask:0xc
	v_add_f32_dpp v49, v57, v57 row_ror:8 row_mask:0xf bank_mask:0xc
	v_add_f32_dpp v50, v58, v58 row_ror:8 row_mask:0xf bank_mask:0xc
	v_add_f32_dpp v51, v59, v59 row_ror:8 row_mask:0xf bank_mask:0xc
	v_add_f32_dpp v52, v60, v60 row_ror:8 row_mask:0xf bank_mask:0xc
	v_add_f32_dpp v53, v61, v61 row_ror:8 row_mask:0xf bank_mask:0xc
	v_add_f32_dpp v54, v62, v62 row_ror:8 row_mask:0xf bank_mask:0xc
	v_add_f32_dpp v55, v63, v63 row_ror:8 row_mask:0xf bank_mask:0xc
	v_add_f32_dpp v48, v48, v48 row_ror:12 row_mask:0xf bank_mask:0x5
	v_add_f32_dpp v49, v49, v49 row_ror:12 row_mask:0xf bank_mask:0x5
	v_add_f32_dpp v50, v50, v50 row_ror:12 row_mask:0xf bank_mask:0x5
	v_add_f32_dpp v51, v51, v51 row_ror:12 row_mask:0xf bank_mask:0x5
	v_add_f32_dpp v48, v52, v52 row_ror:4 row_mask:0xf bank_mask:0xa
	v_add_f32_dpp v49, v53, v53 row_ror:4 row_mask:0xf bank_mask:0xa
	v_add_f32_dpp v50, v54, v54 row_ror:4 row_mask:0xf bank_mask:0xa
	v_add_f32_dpp v51, v55, v55 row_ror:4 row_mask:0xf bank_mask:0xa
	v_add_f32_dpp v64, v48, v48 quad_perm:[2,3,0,1] row_mask:0xf bank_mask:0xf bound_ctrl:1
	v_add_f32_dpp v65, v50, v50 quad_perm:[2,3,0,1] row_mask:0xf bank_mask:0xf bound_ctrl:1
	v_cndmask_b32_e64 v56, v64, v65, s[50:51]
	v_add_f32_dpp v64, v49, v49 quad_perm:[2,3,0,1] row_mask:0xf bank_mask:0xf bound_ctrl:1
	v_add_f32_dpp v65, v51, v51 quad_perm:[2,3,0,1] row_mask:0xf bank_mask:0xf bound_ctrl:1
	v_cndmask_b32_e64 v57, v64, v65, s[50:51]
	v_add_f32_dpp v64, v56, v56 quad_perm:[1,0,3,2] row_mask:0xf bank_mask:0xf bound_ctrl:1
	s_nop 0
	v_add_f32_dpp v65, v57, v57 quad_perm:[1,0,3,2] row_mask:0xf bank_mask:0xf bound_ctrl:1
	v_cndmask_b32_e64 v66, v64, v65, s[48:49]
	v_cvt_pk_bf16_f32 v66, v66, v66
	global_store_short v8, v66, s[12:13]
	s_add_u32 s12, s12, 0x8000
	s_addc_u32 s13, s13, 0

; #define RW_DMA4(B) RW_DMA_ONLY(B); RW_DMA_ONLY((B) + 1); RW_DMA_ONLY((B) + 2); RW_DMA_ONLY((B) + 3)
; template <int DIR>
; DEVINL void rwkv_scan_dir(const Params& p, int task, int lane, int wave) {
;     ...
;   const char* recbase = p.ws + O_REC + ((long)(b * 16 + head) * 4096) * 1024 + lane * 16;
;   const unsigned ring_lds = (unsigned)(unsigned long)(__attribute__((address_space(3))) char*)(dynsmem + wave * 32768);
;   const unsigned ring_u = __builtin_amdgcn_readfirstlane(ring_lds);
;   const unsigned a_seg = ring_lds + seg * 64;
;   const unsigned a_v = ring_lds + (row >> 2) * 64 + 48 + (row & 3) * 2;
;   u16* yo = (u16*)(p.ws + (DIR ? O_YB : O_YSUM)) + ((long)b * 4096) * 1024 + head * 64 + row;
;   float s0 = 0.f, s1 = 0.f, s2 = 0.f, s3 = 0.f;
;   float ykeep = 0.f;
;   const char* recdir = recbase + (DIR ? (long)4095 * 1024 : 0);
;     ...
;   RW_DMA4(0); RW_DMA4(4); RW_DMA4(8); RW_DMA4(12); RW_DMA4(16); RW_DMA4(20);
.Lrw_bwd:
	s_add_u32 s12, s12, 0x1f700000
	s_addc_u32 s13, s13, 0
	v_sub_u32_e32 v69, 0xfff, v3
	v_lshl_add_u32 v8, v69, 11, v8
	s_add_u32 s10, s10, 0x3ff000
	s_addc_u32 s11, s11, 0
	s_sub_u32 s10, s10, s39
	s_subb_u32 s11, s11, 0
	s_sub_u32 s40, 0x1f000, s39
	s_mov_b32 s41, 0
	v_lshlrev_b32_e32 v6, 4, v3
	v_add_u32_e32 v6, 0x1c000, v6
	s_add_u32 s3, s37, 0x1c300
	v_lshl_add_u32 v7, v4, 1, s3
	s_add_u32 s3, s40, s41
	s_and_b32 s3, s3, 0x1ffff
	s_add_u32 s3, s3, 16
	s_mov_b32 m0, s3
	s_nop 0
	global_load_lds_dwordx4 v5, s[10:11] offset:0 nt
	global_load_lds_dwordx4 v5, s[10:11] offset:1024 nt
	global_load_lds_dwordx4 v5, s[10:11] offset:2048 nt
	global_load_lds_dwordx4 v5, s[10:11] offset:3072 nt
	s_sub_u32 s10, s10, 0x4000
	s_subb_u32 s11, s11, 0
	s_sub_u32 s41, s41, 0x4000
	s_and_b32 s41, s41, 0x1ffff
	s_add_u32 s3, s40, s41
	s_and_b32 s3, s3, 0x1ffff
	s_add_u32 s3, s3, 16
	s_mov_b32 m0, s3
	s_nop 0
	global_load_lds_dwordx4 v5, s[10:11] offset:0 nt
	global_load_lds_dwordx4 v5, s[10:11] offset:1024 nt
	global_load_lds_dwordx4 v5, s[10:11] offset:2048 nt
	global_load_lds_dwordx4 v5, s[10:11] offset:3072 nt
	s_sub_u32 s10, s10, 0x4000
	s_subb_u32 s11, s11, 0
	s_sub_u32 s41, s41, 0x4000
	s_and_b32 s41, s41, 0x1ffff
	s_add_u32 s3, s40, s41
	s_and_b32 s3, s3, 0x1ffff
	s_add_u32 s3, s3, 16
	s_mov_b32 m0, s3
	s_nop 0
	global_load_lds_dwordx4 v5, s[10:11] offset:0 nt
	global_load_lds_dwordx4 v5, s[10:11] offset:1024 nt
	global_load_lds_dwordx4 v5, s[10:11] offset:2048 nt
	global_load_lds_dwordx4 v5, s[10:11] offset:3072 nt
	s_sub_u32 s10, s10, 0x4000
	s_subb_u32 s11, s11, 0
	s_sub_u32 s41, s41, 0x4000
	s_and_b32 s41, s41, 0x1ffff
	s_waitcnt vmcnt(0)
	v_mov_b32_e32 v10, 0
	v_mov_b32_e32 v11, 0
	v_mov_b32_e32 v12, 0
	v_mov_b32_e32 v13, 0
	s_mov_b32 s14, 0
	s_add_u32 s3, s15, 3
	v_mov_b32_e32 v69, s3
	ds_write_b32 v23, v69
	s_add_u32 s43, s15, 2
	s_sub_u32 s44, s15, 4
	s_max_i32 s44, s44, 0
	s_mov_b32 s42, 0

.Lrw_ready_d1:
	s_add_u32 s3, s40, s41
	s_and_b32 s3, s3, 0x1ffff
	s_add_u32 s3, s3, 16
	s_mov_b32 m0, s3
	s_nop 0
	global_load_lds_dwordx4 v5, s[10:11] offset:0 nt
	global_load_lds_dwordx4 v5, s[10:11] offset:1024 nt
	global_load_lds_dwordx4 v5, s[10:11] offset:2048 nt
	global_load_lds_dwordx4 v5, s[10:11] offset:3072 nt
	s_sub_u32 s10, s10, 0x4000
	s_subb_u32 s11, s11, 0
	s_sub_u32 s41, s41, 0x4000
	s_and_b32 s41, s41, 0x1ffff
	ds_read_b64 v[72:73], v6 offset:13336
	ds_read_b128 v[74:77], v6 offset:13584
	ds_read_b128 v[78:81], v6 offset:13840
	ds_read_u16 v82, v7 offset:13328
	v_fma_mix_f32 v14, v10, v26, 0 op_sel:[0,0,0] op_sel_hi:[0,1,0]
	v_fma_mix_f32 v63, v10, v92, 0 op_sel:[0,0,0] op_sel_hi:[0,1,0]
	v_fma_mix_f32 v14, v11, v26, v14 op_sel:[0,1,0] op_sel_hi:[0,1,0]
	v_fma_mix_f32 v63, v11, v92, v63 op_sel:[0,1,0] op_sel_hi:[0,1,0]
	v_fma_mix_f32 v14, v12, v27, v14 op_sel:[0,0,0] op_sel_hi:[0,1,0]
	v_fma_mix_f32 v63, v12, v93, v63 op_sel:[0,0,0] op_sel_hi:[0,1,0]
	v_fma_mix_f32 v14, v13, v27, v14 op_sel:[0,1,0] op_sel_hi:[0,1,0]
	v_fma_mix_f32 v16, v10, v24, 0 op_sel:[0,0,0] op_sel_hi:[0,1,0]
	v_fma_mix_f32 v17, v11, v24, 0 op_sel:[0,1,0] op_sel_hi:[0,1,0]
	v_add_f32_dpp v20, v14, v14 quad_perm:[1,0,3,2] row_mask:0xf bank_mask:0xf bound_ctrl:1
	v_fma_mix_f32 v63, v13, v93, v63 op_sel:[0,1,0] op_sel_hi:[0,1,0]
	v_fma_mix_f32 v18, v12, v25, 0 op_sel:[0,0,0] op_sel_hi:[0,1,0]
	v_add_f32_dpp v20, v20, v20 quad_perm:[2,3,0,1] row_mask:0xf bank_mask:0xf bound_ctrl:1
	v_fma_mix_f32 v19, v13, v25, 0 op_sel:[0,1,0] op_sel_hi:[0,1,0]
	v_fma_mix_f32 v16, v34, v30, v16 op_sel:[0,0,0] op_sel_hi:[1,1,0]
	v_add_f32_dpp v20, v20, v20 row_half_mirror row_mask:0xf bank_mask:0xf bound_ctrl:1
	v_fma_mix_f32 v17, v34, v30, v17 op_sel:[0,1,0] op_sel_hi:[1,1,0]
	v_fma_mix_f32 v18, v34, v31, v18 op_sel:[0,0,0] op_sel_hi:[1,1,0]
	v_add_f32_dpp v20, v20, v20 row_mirror row_mask:0xf bank_mask:0xf bound_ctrl:1
	v_fma_mix_f32 v19, v34, v31, v19 op_sel:[0,1,0] op_sel_hi:[1,1,0]
	v_fma_mix_f32 v10, v20, v28, v16 op_sel:[0,0,0] op_sel_hi:[0,1,0]
	v_fma_mix_f32 v11, v20, v28, v17 op_sel:[0,1,0] op_sel_hi:[0,1,0]
	v_fma_mix_f32 v12, v20, v29, v18 op_sel:[0,0,0] op_sel_hi:[0,1,0]
	v_fma_mix_f32 v13, v20, v29, v19 op_sel:[0,1,0] op_sel_hi:[0,1,0]
	s_waitcnt lgkmcnt(4)
	s_cmp_eq_u32 s14, 0
	s_cbranch_scc1 .Lrw_skip_d1
	v_add_f32_dpp v48, v48, v48 row_ror:8 row_mask:0xf bank_mask:0x3
	v_add_f32_dpp v49, v49, v49 row_ror:8 row_mask:0xf bank_mask:0x3
	v_add_f32_dpp v50, v50, v50 row_ror:8 row_mask:0xf bank_mask:0x3
	v_add_f32_dpp v51, v51, v51 row_ror:8 row_mask:0xf bank_mask:0x3
	v_add_f32_dpp v52, v52, v52 row_ror:8 row_mask:0xf bank_mask:0x3
	v_add_f32_dpp v53, v53, v53 row_ror:8 row_mask:0xf bank_mask:0x3
	v_add_f32_dpp v54, v54, v54 row_ror:8 row_mask:0xf bank_mask:0x3
	v_add_f32_dpp v55, v55, v55 row_ror:8 row_mask:0xf bank_mask:0x3
	v_add_f32_dpp v48, v56, v56 row_ror:8 row_mask:0xf bank_mask:0xc
	v_add_f32_dpp v49, v57, v57 row_ror:8 row_mask:0xf bank_mask:0xc
	v_add_f32_dpp v50, v58, v58 row_ror:8 row_mask:0xf bank_mask:0xc
	v_add_f32_dpp v51, v59, v59 row_ror:8 row_mask:0xf bank_mask:0xc
	v_add_f32_dpp v52, v60, v60 row_ror:8 row_mask:0xf bank_mask:0xc
	v_add_f32_dpp v53, v61, v61 row_ror:8 row_mask:0xf bank_mask:0xc
	v_add_f32_dpp v54, v62, v62 row_ror:8 row_mask:0xf bank_mask:0xc
	v_add_f32_dpp v55, v63, v63 row_ror:8 row_mask:0xf bank_mask:0xc
	v_add_f32_dpp v48, v48, v48 row_ror:12 row_mask:0xf bank_mask:0x5
	v_add_f32_dpp v49, v49, v49 row_ror:12 row_mask:0xf bank_mask:0x5
	v_add_f32_dpp v50, v50, v50 row_ror:12 row_mask:0xf bank_mask:0x5
	v_add_f32_dpp v51, v51, v51 row_ror:12 row_mask:0xf bank_mask:0x5
	v_add_f32_dpp v48, v52, v52 row_ror:4 row_mask:0xf bank_mask:0xa
	v_add_f32_dpp v49, v53, v53 row_ror:4 row_mask:0xf bank_mask:0xa
	v_add_f32_dpp v50, v54, v54 row_ror:4 row_mask:0xf bank_mask:0xa
	v_add_f32_dpp v51, v55, v55 row_ror:4 row_mask:0xf bank_mask:0xa
	v_add_f32_dpp v64, v48, v48 quad_perm:[2,3,0,1] row_mask:0xf bank_mask:0xf bound_ctrl:1
	v_add_f32_dpp v65, v50, v50 quad_perm:[2,3,0,1] row_mask:0xf bank_mask:0xf bound_ctrl:1
	v_cndmask_b32_e64 v56, v64, v65, s[50:51]
	v_add_f32_dpp v64, v49, v49 quad_perm:[2,3,0,1] row_mask:0xf bank_mask:0xf bound_ctrl:1
	v_add_f32_dpp v65, v51, v51 quad_perm:[2,3,0,1] row_mask:0xf bank_mask:0xf bound_ctrl:1
	v_cndmask_b32_e64 v57, v64, v65, s[50:51]
	v_add_f32_dpp v64, v56, v56 quad_perm:[1,0,3,2] row_mask:0xf bank_mask:0xf bound_ctrl:1
	s_nop 0
	v_add_f32_dpp v65, v57, v57 quad_perm:[1,0,3,2] row_mask:0xf bank_mask:0xf bound_ctrl:1
	v_cndmask_b32_e64 v66, v64, v65, s[48:49]
	v_cvt_pk_bf16_f32 v66, v66, v66
	global_store_short v8, v66, s[12:13]
	s_sub_u32 s12, s12, 0x8000
	s_subb_u32 s13, s13, 0
